# first grid-barrier census issues its 16 counter loads before one wait; pos-bias partial-sum prep item after the down GEMM issues its 16 w1 loads per step before consuming them (same fma order)
# baseline (speedup 1.0000x reference)
.LBB0_180:
	v_readlane_b32 s4, v253, 16
	v_readlane_b32 s5, v253, 17
	v_readlane_b32 s1, v254, 31
	s_mov_b64 s[8:9], -1
	s_mov_b64 s[10:11], -1
	s_nop 1
	global_load_dword v0, v1, s[4:5] sc1
	v_readlane_b32 s4, v253, 18
	v_readlane_b32 s5, v253, 19
	s_waitcnt lgkmcnt(0)
	s_nop 3
	global_load_dword v2, v1, s[4:5] sc1
	v_readlane_b32 s4, v253, 20
	v_readlane_b32 s5, v253, 21
	s_nop 4
	global_load_dword v3, v1, s[4:5] sc1
	v_readlane_b32 s4, v253, 22
	v_readlane_b32 s5, v253, 23
	s_nop 4
	global_load_dword v4, v1, s[4:5] sc1
	v_readlane_b32 s4, v253, 24
	v_readlane_b32 s5, v253, 25
	s_nop 4
	global_load_dword v5, v1, s[4:5] sc1
	v_readlane_b32 s4, v253, 26
	v_readlane_b32 s5, v253, 27
	s_nop 4
	global_load_dword v6, v1, s[4:5] sc1
	v_readlane_b32 s4, v253, 28
	v_readlane_b32 s5, v253, 29
	s_nop 4
	global_load_dword v7, v1, s[4:5] sc1
	v_readlane_b32 s4, v253, 30
	v_readlane_b32 s5, v253, 31
	s_nop 4
	global_load_dword v8, v1, s[4:5] sc1
	v_readlane_b32 s4, v253, 32
	v_readlane_b32 s5, v253, 33
	s_nop 4
	global_load_dword v9, v1, s[4:5] sc1
	v_readlane_b32 s4, v253, 34
	v_readlane_b32 s5, v253, 35
	s_nop 4
	global_load_dword v10, v1, s[4:5] sc1
	v_readlane_b32 s4, v253, 36
	v_readlane_b32 s5, v253, 37
	s_nop 4
	global_load_dword v11, v1, s[4:5] sc1
	v_readlane_b32 s4, v253, 38
	v_readlane_b32 s5, v253, 39
	s_nop 4
	global_load_dword v12, v1, s[4:5] sc1
	v_readlane_b32 s4, v253, 40
	v_readlane_b32 s5, v253, 41
	s_nop 4
	global_load_dword v13, v1, s[4:5] sc1
	v_readlane_b32 s4, v253, 42
	v_readlane_b32 s5, v253, 43
	s_nop 4
	global_load_dword v14, v1, s[4:5] sc1
	v_readlane_b32 s4, v253, 44
	v_readlane_b32 s5, v253, 45
	s_nop 4
	global_load_dword v15, v1, s[4:5] sc1
	v_readlane_b32 s4, v253, 46
	v_readlane_b32 s5, v253, 47
	s_nop 4
	global_load_dword v16, v1, s[4:5] sc1
	s_waitcnt vmcnt(0)
	v_add_u32_e32 v17, v2, v0
	v_add_u32_e32 v17, v17, v3
	v_add_u32_e32 v17, v17, v4
	v_add_u32_e32 v17, v17, v5
	v_add_u32_e32 v17, v17, v6
	v_add_u32_e32 v17, v17, v7
	v_add_u32_e32 v17, v17, v8
	v_add_u32_e32 v17, v17, v9
	v_add_u32_e32 v17, v17, v10
	v_add_u32_e32 v17, v17, v11
	v_add_u32_e32 v17, v17, v12
	v_add_u32_e32 v17, v17, v13
	v_add_u32_e32 v17, v17, v14
	v_add_u32_e32 v17, v17, v15
	v_add_u32_e32 v17, v17, v16
	v_cmp_eq_u32_e32 vcc, s1, v17
	s_cbranch_vccnz .LBB0_179
	s_and_b32 s1, s0, 0xff
	s_cmp_eq_u32 s1, 0
	s_mov_b64 s[12:13], -1
	s_sleep 1
	s_cbranch_scc0 .LBB0_184
	v_readlane_b32 s4, v253, 14
	v_readlane_b32 s5, v253, 15
	s_nop 4
	global_load_dword v17, v1, s[4:5] sc1
	s_waitcnt vmcnt(0)
	v_cmp_eq_u32_e32 vcc, 0, v17
	s_cbranch_vccnz .LBB0_186
	s_mov_b64 s[12:13], 0

.LBB0_795:
	v_lshl_add_u64 v[20:21], s[52:53], 0, v[0:1]
	s_mov_b32 s25, 0x200000
	s_add_u32 s56, s18, s54
	v_add_co_u32_e32 v22, vcc, s25, v20
	s_addc_u32 s57, s19, s55
	s_nop 0
	v_addc_co_u32_e32 v23, vcc, 0, v21, vcc
	s_mov_b32 s25, 0x201000
	s_add_u32 s58, s56, 0x2000
	v_add_co_u32_e32 v24, vcc, s25, v20
	s_addc_u32 s59, s57, 0
	v_mov_b32_e32 v7, 0x2000
	v_addc_co_u32_e32 v25, vcc, 0, v21, vcc
	global_load_dwordx4 v[2:5], v1, s[58:59] offset:48
	global_load_dwordx4 v[8:11], v1, s[58:59] offset:32
	global_load_dwordx4 v[12:15], v1, s[58:59] offset:16
	global_load_dwordx4 v[16:19], v7, s[56:57]
	s_mov_b32 s25, 0x202000
	v_add_co_u32_e32 v90, vcc, s25, v20
	s_nop 1
	v_addc_co_u32_e32 v91, vcc, 0, v21, vcc
	s_mov_b32 s25, 0x203000
	v_add_co_u32_e32 v92, vcc, s25, v20
	s_nop 1
	v_addc_co_u32_e32 v93, vcc, 0, v21, vcc
	v_lshl_add_u64 v[94:95], s[40:41], 0, v[0:1]
	global_load_dword v96, v[24:25], off offset:-4096
	global_load_dword v97, v[22:23], off offset:1024
	global_load_dword v98, v[22:23], off offset:2048
	global_load_dword v99, v[22:23], off offset:3072
	global_load_dword v100, v[24:25], off
	global_load_dword v101, v[24:25], off offset:1024
	global_load_dword v102, v[24:25], off offset:2048
	global_load_dword v103, v[24:25], off offset:3072
	global_load_dword v104, v[92:93], off offset:-4096
	global_load_dword v105, v[90:91], off offset:1024
	global_load_dword v106, v[90:91], off offset:2048
	global_load_dword v107, v[90:91], off offset:3072
	global_load_dword v108, v[92:93], off
	global_load_dword v109, v[92:93], off offset:1024
	global_load_dword v110, v[92:93], off offset:2048
	global_load_dword v111, v[94:95], off
	s_add_u32 s40, s40, 0x4000
	s_addc_u32 s41, s41, 0
	s_add_u32 s52, s52, 0x4000
	s_addc_u32 s53, s53, 0
	s_add_u32 s54, s54, 64
	s_addc_u32 s55, s55, 0
	s_cmpk_eq_i32 s54, 0x100
	s_waitcnt vmcnt(15)
	v_fmac_f32_e32 v6, v16, v96
	s_waitcnt vmcnt(14)
	v_fmac_f32_e32 v6, v17, v97
	s_waitcnt vmcnt(13)
	v_fmac_f32_e32 v6, v18, v98
	s_waitcnt vmcnt(12)
	v_fmac_f32_e32 v6, v19, v99
	s_waitcnt vmcnt(11)
	v_fmac_f32_e32 v6, v12, v100
	s_waitcnt vmcnt(10)
	v_fmac_f32_e32 v6, v13, v101
	s_waitcnt vmcnt(9)
	v_fmac_f32_e32 v6, v14, v102
	s_waitcnt vmcnt(8)
	v_fmac_f32_e32 v6, v15, v103
	s_waitcnt vmcnt(7)
	v_fmac_f32_e32 v6, v8, v104
	s_waitcnt vmcnt(6)
	v_fmac_f32_e32 v6, v9, v105
	s_waitcnt vmcnt(5)
	v_fmac_f32_e32 v6, v10, v106
	s_waitcnt vmcnt(4)
	v_fmac_f32_e32 v6, v11, v107
	s_waitcnt vmcnt(3)
	v_fmac_f32_e32 v6, v2, v108
	s_waitcnt vmcnt(2)
	v_fmac_f32_e32 v6, v3, v109
	s_waitcnt vmcnt(1)
	v_fmac_f32_e32 v6, v4, v110
	s_waitcnt vmcnt(0)
	v_fmac_f32_e32 v6, v5, v111
	s_cbranch_scc0 .LBB0_795
	s_lshl_b32 s18, s2, 6
	s_lshl_b32 s15, s15, 6
	s_and_b32 s18, s18, 0xc0
	s_lshl_b32 s16, s16, 13
	s_and_b32 s15, s15, 0x1f00
	v_or_b32_e32 v0, s18, v70
	s_or_b32 s15, s15, s16
	v_or_b32_e32 v0, s15, v0
	v_lshl_add_u64 v[2:3], v[0:1], 2, s[20:21]
	s_mov_b64 s[40:41], 0
	global_store_dword v[2:3], v6, off
